# baseline (speedup 1.0000x reference)
.LBB0_99:
	v_ashrrev_i32_e32 v37, 31, v36
	v_lshl_add_u64 v[18:19], v[36:37], 4, s[10:11]
	v_lshlrev_b64 v[20:21], 11, v[36:37]
	v_lshl_add_u64 v[30:31], v[22:23], 0, v[20:21]
	global_load_dwordx4 v[18:21], v[18:19], off
	s_nop 0
	global_load_dwordx2 v[46:47], v[30:31], off nt
	global_load_dwordx2 v[44:45], v[30:31], off offset:512 nt
	global_load_dwordx2 v[40:41], v[30:31], off offset:1024 nt
	global_load_dwordx2 v[38:39], v[30:31], off offset:1536 nt
	v_add_u32_e32 v30, s98, v36
	v_cmp_gt_i32_e32 vcc, s91, v30
	v_ashrrev_i32_e32 v31, 31, v30
	v_mov_b32_e32 v42, 0
	s_and_saveexec_b64 s[12:13], vcc
	s_cbranch_execz .LBB0_101
	v_lshl_add_u64 v[26:27], v[30:31], 4, s[10:11]
	global_load_dwordx4 v[52:55], v[26:27], off
	v_lshlrev_b64 v[26:27], 11, v[30:31]
	v_lshl_add_u64 v[34:35], v[22:23], 0, v[26:27]
	global_load_dwordx2 v[26:27], v[34:35], off nt
	global_load_dwordx2 v[28:29], v[34:35], off offset:512 nt
	global_load_dwordx2 v[32:33], v[34:35], off offset:1024 nt
	s_nop 0
	global_load_dwordx2 v[34:35], v[34:35], off offset:1536 nt
	s_waitcnt vmcnt(4)
	v_add_f32_e32 v1, v52, v53
	v_add_f32_e32 v1, v54, v1
	v_add_f32_e32 v1, v55, v1
	v_fmamk_f32 v1, v1, 0x3a800000, v208
	v_cmp_gt_f32_e64 s[4:5], s95, v1
	v_mul_f32_e32 v56, 0x4b800000, v1
	s_nop 0
	v_cndmask_b32_e64 v1, v1, v56, s[4:5]
	v_rsq_f32_e32 v1, v1
	s_nop 0
	v_mul_f32_e32 v42, 0x45800000, v1
	v_cndmask_b32_e64 v42, v1, v42, s[4:5]

.LBB0_539:
	v_mad_i64_i32 v[6:7], s[4:5], s8, v6, 0
	s_lshl_b32 s4, s12, 6
	v_lshl_add_u64 v[6:7], v[6:7], 1, s[6:7]
	s_ashr_i32 s5, s4, 31
	v_lshl_add_u64 v[6:7], s[4:5], 1, v[6:7]
	v_lshlrev_b32_e32 v8, 1, v1
	v_mov_b32_e32 v9, v0
	v_lshl_add_u64 v[6:7], v[6:7], 0, v[8:9]
	global_store_dwordx4 v[6:7], v[2:5], off nt
	s_xor_b32 s33, s33, 1
	s_andn2_b64 vcc, exec, s[30:31]
	s_mov_b32 s39, s38
	s_waitcnt vmcnt(1)
	v_mov_b32_e32 v2, v10
	v_mov_b32_e32 v3, v11
	v_mov_b32_e32 v4, v12
	v_mov_b32_e32 v5, v13
	v_mov_b32_e32 v6, v14
	v_mov_b32_e32 v7, v15
	v_mov_b32_e32 v8, v16
	v_mov_b32_e32 v9, v17
	v_mul_f32_e32 v18, v55, v22
	v_mul_f32_e32 v20, v55, v23
	s_cbranch_vccz .LBB0_623
